# record builder stores (170 MB of chunk records written once) non-temporal
# baseline (speedup 1.0000x reference)
.LBB0_321:
	s_movk_i32 s1, 0x440
	v_mad_u32_u24 v3, v17, s1, v2
	v_add_u32_e32 v3, 0x1000, v3
	v_mul_u32_u24_e32 v1, 0x110, v17
	ds_read2_b32 v[18:19], v3 offset0:64 offset1:80
	v_mad_u32_u24 v3, v14, s29, v2
	v_add_u32_e32 v3, 0x1000, v3
	v_add_u32_e32 v11, v2, v1
	ds_read2_b32 v[24:25], v3 offset0:64 offset1:80
	ds_read2_b32 v[14:15], v3 offset0:132 offset1:148
	ds_read2_b32 v[26:27], v3 offset0:200 offset1:216
	v_add_u32_e32 v2, 0x3000, v11
	ds_read2_b32 v[32:33], v2 offset0:192 offset1:208
	s_waitcnt lgkmcnt(4)
	v_mov_b32_e32 v28, v18
	s_waitcnt lgkmcnt(3)
	v_mov_b32_e32 v29, v24
	s_waitcnt lgkmcnt(2)
	v_mov_b32_e32 v30, v14
	s_waitcnt lgkmcnt(1)
	v_mov_b32_e32 v31, v26
	v_add_u32_e32 v2, 0x3400, v11
	ds_read2_b32 v[34:35], v2 offset0:208 offset1:224
	s_waitcnt lgkmcnt(1)
	v_mfma_f32_16x16x4_f32 v[28:31], v6, v32, v[28:31]
	v_add_u32_e32 v2, 0x3800, v11
	ds_read2_b32 v[36:37], v2 offset0:224 offset1:240
	v_mov_b32_e32 v24, v19
	v_mov_b32_e32 v26, v15
	v_lshl_add_u32 v10, s0, 2, v10
	v_lshl_add_u64 v[2:3], s[12:13], 0, v[156:157]
	s_mov_b64 s[2:3], 0x2d80
	s_waitcnt lgkmcnt(1)
	v_mfma_f32_16x16x4_f32 v[28:31], v7, v34, v[28:31]
	v_lshl_add_u32 v48, v17, 2, s16
	v_lshl_add_u64 v[14:15], v[2:3], 0, s[2:3]
	v_add_u32_e32 v1, v22, v1
	v_add_u32_e32 v23, 0x3000, v1
	v_mul_u32_u24_e32 v12, 24, v12
	v_lshrrev_b32_e32 v44, 1, v16
	v_and_b32_e32 v45, 8, v106
	v_mfma_f32_16x16x4_f32 v[24:27], v6, v33, v[24:27]
	v_add_u32_e32 v6, 0x3e00, v11
	ds_read2_b32 v[18:19], v6 offset0:112 offset1:128
	v_lshl_add_u32 v6, v9, 2, s16
	ds_read_b32 v6, v6 offset:27904
	ds_read_b32 v32, v10 offset:27968
	v_mul_u32_u24_e32 v9, 24, v9
	v_lshlrev_b32_e32 v156, 1, v9
	v_add_u32_e32 v49, 0x6c00, v22
	s_waitcnt lgkmcnt(3)
	v_mfma_f32_16x16x4_f32 v[28:31], v4, v36, v[28:31]
	v_lshl_add_u64 v[46:47], v[2:3], 0, s[30:31]
	s_movk_i32 s0, 0x3000
	s_add_i32 s8, s8, s9
	v_mfma_f32_16x16x4_f32 v[24:27], v7, v35, v[24:27]
	s_waitcnt lgkmcnt(2)
	v_mfma_f32_16x16x4_f32 v[28:31], v5, v18, v[28:31]
	v_mfma_f32_16x16x4_f32 v[24:27], v4, v37, v[24:27]
	s_nop 8
	v_mov_b32_e32 v10, v28
	v_mov_b32_e32 v11, v30
	v_mov_b32_e32 v30, v29
	s_waitcnt lgkmcnt(1)
	v_mul_f32_e64 v10, v10, v6
	v_mul_f32_e64 v11, v11, v6
	v_pk_mul_f32 v[28:29], v[30:31], v[6:7] op_sel_hi:[1,0]
	v_and_b32_sdwa v6, v11, v195 dst_sel:DWORD dst_unused:UNUSED_PAD src0_sel:WORD_1 src1_sel:DWORD
	v_and_b32_sdwa v13, v10, v195 dst_sel:DWORD dst_unused:UNUSED_PAD src0_sel:WORD_1 src1_sel:DWORD
	v_add3_u32 v10, v10, v13, s54
	v_add3_u32 v6, v11, v6, s54
	v_and_b32_sdwa v11, v29, v195 dst_sel:DWORD dst_unused:UNUSED_PAD src0_sel:WORD_1 src1_sel:DWORD
	v_and_b32_sdwa v13, v28, v195 dst_sel:DWORD dst_unused:UNUSED_PAD src0_sel:WORD_1 src1_sel:DWORD
	v_add3_u32 v7, v29, v11, s54
	v_add3_u32 v11, v28, v13, s54
	v_and_b32_e32 v7, 0xffff0000, v7
	v_and_b32_e32 v11, 0xffff0000, v11
	v_add_u32_e32 v4, v48, v8
	v_or_b32_sdwa v7, v7, v6 dst_sel:DWORD dst_unused:UNUSED_PAD src0_sel:DWORD src1_sel:WORD_1
	v_or_b32_sdwa v6, v11, v10 dst_sel:DWORD dst_unused:UNUSED_PAD src0_sel:DWORD src1_sel:WORD_1
	v_lshl_add_u64 v[10:11], v[14:15], 0, v[156:157]
	v_add_u32_e32 v13, 0x5c00, v4
	global_store_dwordx2 v[10:11], v[6:7], off nt
	ds_read2_b32 v[40:41], v13 offset1:4
	v_mfma_f32_16x16x4_f32 v[4:7], v5, v19, v[24:27]
	ds_read2_b32 v[10:11], v23 offset0:192 offset1:208
	ds_read2_b32 v[42:43], v13 offset0:8 offset1:12
	v_lshlrev_b32_e32 v156, 1, v12
	v_lshlrev_b32_e32 v12, 8, v45
	s_nop 5
	v_mov_b32_e32 v8, v4
	v_mov_b32_e32 v9, v6
	v_mov_b32_e32 v6, v5
	s_waitcnt lgkmcnt(3)
	v_pk_mul_f32 v[18:19], v[8:9], v[32:33] op_sel_hi:[1,0]
	v_pk_mul_f32 v[28:29], v[6:7], v[32:33] op_sel_hi:[1,0]
	s_waitcnt lgkmcnt(1)
	v_mfma_f32_16x16x4_f32 v[6:9], v40, v10, 0
	v_add_u32_e32 v4, 0x3400, v1
	ds_read2_b32 v[4:5], v4 offset0:208 offset1:224
	v_and_b32_sdwa v24, v18, v195 dst_sel:DWORD dst_unused:UNUSED_PAD src0_sel:WORD_1 src1_sel:DWORD
	v_add3_u32 v18, v18, v24, s54
	v_and_b32_sdwa v17, v19, v195 dst_sel:DWORD dst_unused:UNUSED_PAD src0_sel:WORD_1 src1_sel:DWORD
	v_add3_u32 v17, v19, v17, s54
	s_waitcnt lgkmcnt(0)
	v_mfma_f32_16x16x4_f32 v[24:27], v41, v4, v[6:9]
	s_nop 1
	v_and_b32_sdwa v8, v29, v195 dst_sel:DWORD dst_unused:UNUSED_PAD src0_sel:WORD_1 src1_sel:DWORD
	v_and_b32_sdwa v9, v28, v195 dst_sel:DWORD dst_unused:UNUSED_PAD src0_sel:WORD_1 src1_sel:DWORD
	v_add3_u32 v8, v29, v8, s54
	v_add3_u32 v9, v28, v9, s54
	v_and_b32_e32 v13, 0xffff0000, v8
	v_and_b32_e32 v28, 0xffff0000, v9
	v_or_b32_sdwa v19, v13, v17 dst_sel:DWORD dst_unused:UNUSED_PAD src0_sel:DWORD src1_sel:WORD_1
	v_lshlrev_b32_e32 v13, 2, v44
	v_or_b32_sdwa v18, v28, v18 dst_sel:DWORD dst_unused:UNUSED_PAD src0_sel:DWORD src1_sel:WORD_1
	v_lshl_add_u64 v[28:29], v[14:15], 0, v[156:157]
	v_add3_u32 v32, s16, v12, v13
	v_mfma_f32_16x16x4_f32 v[12:15], v40, v11, 0
	v_add_u32_e32 v6, 0x3800, v1
	ds_read2_b32 v[6:7], v6 offset0:224 offset1:240
	v_add_u32_e32 v8, 0x3e00, v1
	ds_read2st64_b32 v[16:17], v32 offset0:110 offset1:111
	ds_read2_b32 v[8:9], v8 offset0:112 offset1:128
	global_store_dwordx2 v[28:29], v[18:19], off nt
	ds_read2st64_b32 v[18:19], v32 offset0:112 offset1:113
	ds_read2st64_b32 v[30:31], v32 offset0:114 offset1:115
	ds_read2st64_b32 v[36:37], v32 offset0:116 offset1:117
	v_mfma_f32_16x16x4_f32 v[12:15], v41, v5, v[12:15]
	s_waitcnt lgkmcnt(4)
	v_bfe_u32 v28, v16, 16, 1
	v_add3_u32 v16, v16, v28, s54
	v_bfe_u32 v28, v17, 16, 1
	v_lshrrev_b32_e32 v16, 16, v16
	v_add3_u32 v17, v17, v28, s54
	v_and_or_b32 v28, v17, s33, v16
	s_waitcnt lgkmcnt(2)
	v_bfe_u32 v16, v18, 16, 1
	v_mfma_f32_16x16x4_f32 v[12:15], v42, v7, v[12:15]
	v_add3_u32 v16, v18, v16, s54
	v_bfe_u32 v17, v19, 16, 1
	v_lshrrev_b32_e32 v16, 16, v16
	v_add3_u32 v17, v19, v17, s54
	v_and_or_b32 v29, v17, s33, v16
	s_waitcnt lgkmcnt(1)
	v_bfe_u32 v16, v30, 16, 1
	v_add3_u32 v16, v30, v16, s54
	v_mfma_f32_16x16x4_f32 v[24:27], v42, v6, v[24:27]
	v_bfe_u32 v17, v31, 16, 1
	v_lshrrev_b32_e32 v16, 16, v16
	v_add3_u32 v17, v31, v17, s54
	v_and_or_b32 v30, v17, s33, v16
	v_add_u32_e32 v18, 0x3c00, v1
	ds_read2_b32 v[18:19], v18 offset1:16
	v_mfma_f32_16x16x4_f32 v[32:35], v43, v9, v[12:15]
	ds_read2_b32 v[14:15], v23 offset0:224 offset1:240
	s_waitcnt lgkmcnt(2)
	v_bfe_u32 v12, v36, 16, 1
	v_bfe_u32 v13, v37, 16, 1
	v_add3_u32 v12, v36, v12, s54
	v_add3_u32 v13, v37, v13, s54
	v_lshrrev_b32_e32 v12, 16, v12
	v_and_or_b32 v31, v13, s33, v12
	s_waitcnt lgkmcnt(0)
	v_mfma_f32_16x16x4_f32 v[36:39], v40, v14, 0
	v_add_u32_e32 v12, 0x3600, v1
	ds_read2_b32 v[16:17], v12 offset0:112 offset1:128
	v_mul_u32_u24_e32 v12, 24, v44
	v_lshlrev_b32_e32 v156, 1, v12
	v_lshl_add_u64 v[12:13], s[12:13], 0, v[156:157]
	v_lshlrev_b32_e32 v156, 1, v45
	ds_read2_b32 v[44:45], v49 offset0:64 offset1:80
	v_mfma_f32_16x16x4_f32 v[24:27], v43, v8, v[24:27]
	v_lshl_add_u64 v[12:13], v[12:13], 0, v[156:157]
	v_add_co_u32_e32 v12, vcc, s0, v12
	v_add_u32_e32 v1, 0x4000, v1
	s_nop 0
	v_addc_co_u32_e32 v13, vcc, 0, v13, vcc
	global_store_dwordx4 v[12:13], v[28:31], off offset:2432 nt
	s_waitcnt lgkmcnt(1)
	v_mfma_f32_16x16x4_f32 v[36:39], v41, v16, v[36:39]
	s_nop 1
	v_mov_b32_e32 v2, v24
	v_mov_b32_e32 v3, v26
	s_waitcnt lgkmcnt(0)
	v_mul_f32_e64 v2, v2, v44
	v_mul_f32_e64 v3, v3, v44
	v_mov_b32_e32 v26, v25
	v_and_b32_sdwa v22, v2, v195 dst_sel:DWORD dst_unused:UNUSED_PAD src0_sel:WORD_1 src1_sel:DWORD
	v_add3_u32 v2, v2, v22, s54
	ds_read2_b32 v[12:13], v1 offset0:16 offset1:32
	v_mfma_f32_16x16x4_f32 v[22:25], v40, v15, 0
	v_mul_f32_e64 v26, v26, v44
	v_mul_f32_e64 v27, v27, v44
	v_and_b32_sdwa v1, v3, v195 dst_sel:DWORD dst_unused:UNUSED_PAD src0_sel:WORD_1 src1_sel:DWORD
	v_add3_u32 v1, v3, v1, s54
	v_and_b32_sdwa v3, v27, v195 dst_sel:DWORD dst_unused:UNUSED_PAD src0_sel:WORD_1 src1_sel:DWORD
	v_add3_u32 v3, v27, v3, s54
	v_and_b32_e32 v3, 0xffff0000, v3
	v_or_b32_sdwa v3, v3, v1 dst_sel:DWORD dst_unused:UNUSED_PAD src0_sel:DWORD src1_sel:WORD_1
	v_mfma_f32_16x16x4_f32 v[36:39], v42, v18, v[36:39]
	v_mov_b32_e32 v1, v157
	v_or_b32_e32 v40, 16, v20
	v_mov_b32_e32 v27, v34
	v_add_u32_e32 v20, v48, v21
	v_mov_b32_e32 v34, v33
	s_mov_b64 s[0:1], 0x880
	v_mfma_f32_16x16x4_f32 v[22:25], v41, v17, v[22:25]
	s_waitcnt lgkmcnt(0)
	v_mfma_f32_16x16x4_f32 v[28:31], v43, v12, v[36:39]
	s_nop 0
	v_and_b32_sdwa v36, v26, v195 dst_sel:DWORD dst_unused:UNUSED_PAD src0_sel:WORD_1 src1_sel:DWORD
	v_add3_u32 v26, v26, v36, s54
	v_and_b32_e32 v26, 0xffff0000, v26
	v_or_b32_sdwa v2, v26, v2 dst_sel:DWORD dst_unused:UNUSED_PAD src0_sel:DWORD src1_sel:WORD_1
	v_lshl_add_u64 v[36:37], v[46:47], 0, v[0:1]
	v_mov_b32_e32 v26, v32
	v_mov_b32_e32 v32, v45
	global_store_dwordx2 v[36:37], v[2:3], off offset:2944 nt
	v_mfma_f32_16x16x4_f32 v[0:3], v42, v19, v[22:25]
	v_mul_f32_e64 v22, v26, v32
	v_mul_f32_e64 v23, v27, v32
	v_add_u32_e32 v26, 0x5c00, v20
	ds_read2_b32 v[38:39], v26 offset1:4
	v_and_b32_sdwa v20, v23, v195 dst_sel:DWORD dst_unused:UNUSED_PAD src0_sel:WORD_1 src1_sel:DWORD
	v_and_b32_sdwa v21, v22, v195 dst_sel:DWORD dst_unused:UNUSED_PAD src0_sel:WORD_1 src1_sel:DWORD
	v_pk_mul_f32 v[24:25], v[34:35], v[32:33] op_sel_hi:[1,0]
	v_add3_u32 v27, v22, v21, s54
	v_add3_u32 v33, v23, v20, s54
	s_waitcnt lgkmcnt(0)
	v_mfma_f32_16x16x4_f32 v[20:23], v38, v10, 0
	v_and_b32_sdwa v34, v25, v195 dst_sel:DWORD dst_unused:UNUSED_PAD src0_sel:WORD_1 src1_sel:DWORD
	v_and_b32_sdwa v35, v24, v195 dst_sel:DWORD dst_unused:UNUSED_PAD src0_sel:WORD_1 src1_sel:DWORD
	v_add3_u32 v10, v25, v34, s54
	v_add3_u32 v24, v24, v35, s54
	ds_read2_b32 v[34:35], v26 offset0:8 offset1:12
	v_and_b32_e32 v10, 0xffff0000, v10
	v_and_b32_e32 v24, 0xffff0000, v24
	v_mfma_f32_16x16x4_f32 v[20:23], v39, v4, v[20:23]
	v_mul_u32_u24_e32 v4, 0x44, v40
	v_lshlrev_b32_e32 v156, 1, v4
	v_or_b32_sdwa v25, v10, v33 dst_sel:DWORD dst_unused:UNUSED_PAD src0_sel:DWORD src1_sel:WORD_1
	v_or_b32_sdwa v24, v24, v27 dst_sel:DWORD dst_unused:UNUSED_PAD src0_sel:DWORD src1_sel:WORD_1
	v_lshl_add_u64 v[40:41], v[46:47], 0, v[156:157]
	global_store_dwordx2 v[40:41], v[24:25], off offset:2944 nt
	v_mov_b32_e32 v24, v28
	s_waitcnt lgkmcnt(0)
	v_mfma_f32_16x16x4_f32 v[20:23], v34, v6, v[20:23]
	v_mov_b32_e32 v25, v30
	v_mov_b32_e32 v30, v29
	v_mfma_f32_16x16x4_f32 v[0:3], v43, v13, v[0:3]
	ds_read2_b32 v[42:43], v49 offset0:96 offset1:112
	s_waitcnt lgkmcnt(0)
	v_mul_f32_e64 v24, v24, v42
	v_mul_f32_e64 v25, v25, v42
	v_mul_f32_e64 v26, v30, v42
	v_mul_f32_e64 v27, v31, v42
	v_and_b32_sdwa v4, v25, v195 dst_sel:DWORD dst_unused:UNUSED_PAD src0_sel:WORD_1 src1_sel:DWORD
	v_and_b32_sdwa v6, v24, v195 dst_sel:DWORD dst_unused:UNUSED_PAD src0_sel:WORD_1 src1_sel:DWORD
	v_mfma_f32_16x16x4_f32 v[20:23], v35, v8, v[20:23]
	v_and_b32_sdwa v8, v27, v195 dst_sel:DWORD dst_unused:UNUSED_PAD src0_sel:WORD_1 src1_sel:DWORD
	v_and_b32_sdwa v10, v26, v195 dst_sel:DWORD dst_unused:UNUSED_PAD src0_sel:WORD_1 src1_sel:DWORD
	v_add3_u32 v6, v24, v6, s54
	v_add3_u32 v4, v25, v4, s54
	v_add3_u32 v8, v27, v8, s54
	v_add3_u32 v10, v26, v10, s54
	v_and_b32_e32 v8, 0xffff0000, v8
	v_mfma_f32_16x16x4_f32 v[24:27], v38, v11, 0
	v_and_b32_e32 v10, 0xffff0000, v10
	v_or_b32_sdwa v29, v8, v4 dst_sel:DWORD dst_unused:UNUSED_PAD src0_sel:DWORD src1_sel:WORD_1
	v_or_b32_sdwa v28, v10, v6 dst_sel:DWORD dst_unused:UNUSED_PAD src0_sel:DWORD src1_sel:WORD_1
	v_lshl_add_u64 v[10:11], v[40:41], 0, s[0:1]
	global_store_dwordx2 v[10:11], v[28:29], off offset:2944 nt
	v_mov_b32_e32 v28, v0
	v_mov_b32_e32 v29, v2
	v_mfma_f32_16x16x4_f32 v[24:27], v39, v5, v[24:27]
	v_mov_b32_e32 v8, v43
	v_mul_f32_e64 v28, v28, v8
	v_mul_f32_e64 v29, v29, v8
	v_mov_b32_e32 v2, v1
	v_mul_f32_e64 v4, v2, v8
	v_mul_f32_e64 v5, v3, v8
	v_and_b32_sdwa v0, v29, v195 dst_sel:DWORD dst_unused:UNUSED_PAD src0_sel:WORD_1 src1_sel:DWORD
	v_and_b32_sdwa v1, v28, v195 dst_sel:DWORD dst_unused:UNUSED_PAD src0_sel:WORD_1 src1_sel:DWORD
	v_add3_u32 v6, v28, v1, s54
	v_add3_u32 v28, v29, v0, s54
	v_and_b32_sdwa v29, v5, v195 dst_sel:DWORD dst_unused:UNUSED_PAD src0_sel:WORD_1 src1_sel:DWORD
	v_mfma_f32_16x16x4_f32 v[0:3], v34, v7, v[24:27]
	v_and_b32_sdwa v7, v4, v195 dst_sel:DWORD dst_unused:UNUSED_PAD src0_sel:WORD_1 src1_sel:DWORD
	v_add3_u32 v5, v5, v29, s54
	v_add3_u32 v4, v4, v7, s54
	v_and_b32_e32 v5, 0xffff0000, v5
	v_and_b32_e32 v4, 0xffff0000, v4
	s_mov_b64 s[0:1], 0x1100
	v_or_b32_sdwa v5, v5, v28 dst_sel:DWORD dst_unused:UNUSED_PAD src0_sel:DWORD src1_sel:WORD_1
	v_or_b32_sdwa v4, v4, v6 dst_sel:DWORD dst_unused:UNUSED_PAD src0_sel:DWORD src1_sel:WORD_1
	v_lshl_add_u64 v[24:25], v[40:41], 0, s[0:1]
	global_store_dwordx2 v[24:25], v[4:5], off offset:2944 nt
	v_mov_b32_e32 v4, v20
	v_mov_b32_e32 v5, v22
	v_pk_mul_f32 v[26:27], v[44:45], v[4:5] op_sel_hi:[0,1]
	v_mfma_f32_16x16x4_f32 v[4:7], v38, v14, 0
	v_mov_b32_e32 v22, v21
	v_mul_f32_e64 v20, v44, v22
	v_mul_f32_e64 v21, v44, v23
	v_and_b32_sdwa v22, v21, v195 dst_sel:DWORD dst_unused:UNUSED_PAD src0_sel:WORD_1 src1_sel:DWORD
	v_and_b32_sdwa v23, v20, v195 dst_sel:DWORD dst_unused:UNUSED_PAD src0_sel:WORD_1 src1_sel:DWORD
	v_and_b32_sdwa v14, v26, v195 dst_sel:DWORD dst_unused:UNUSED_PAD src0_sel:WORD_1 src1_sel:DWORD
	v_add3_u32 v21, v21, v22, s54
	v_add3_u32 v14, v26, v14, s54
	v_mfma_f32_16x16x4_f32 v[4:7], v39, v16, v[4:7]
	v_add3_u32 v16, v20, v23, s54
	v_and_b32_e32 v20, 0xffff0000, v21
	v_and_b32_e32 v16, 0xffff0000, v16
	v_readlane_b32 s0, v249, 36
	s_add_i32 s22, s22, s0
	s_cmpk_gt_i32 s22, 0x8ff
	v_readlane_b32 s1, v249, 37
	v_mfma_f32_16x16x4_f32 v[0:3], v35, v9, v[0:3]
	v_and_b32_sdwa v9, v27, v195 dst_sel:DWORD dst_unused:UNUSED_PAD src0_sel:WORD_1 src1_sel:DWORD
	v_add3_u32 v9, v27, v9, s54
	v_or_b32_sdwa v21, v20, v9 dst_sel:DWORD dst_unused:UNUSED_PAD src0_sel:DWORD src1_sel:WORD_1
	v_or_b32_sdwa v20, v16, v14 dst_sel:DWORD dst_unused:UNUSED_PAD src0_sel:DWORD src1_sel:WORD_1
	global_store_dwordx2 v[36:37], v[20:21], off offset:2976 nt
	s_nop 4
	v_mov_b32_e32 v20, v0
	v_mfma_f32_16x16x4_f32 v[4:7], v34, v18, v[4:7]
	v_mov_b32_e32 v21, v2
	v_mul_f32_e64 v20, v32, v20
	v_mul_f32_e64 v21, v32, v21
	v_mov_b32_e32 v2, v1
	v_mul_f32_e64 v22, v32, v2
	v_mul_f32_e64 v23, v32, v3
	v_and_b32_sdwa v0, v20, v195 dst_sel:DWORD dst_unused:UNUSED_PAD src0_sel:WORD_1 src1_sel:DWORD
	v_add3_u32 v14, v20, v0, s54
	v_and_b32_sdwa v9, v21, v195 dst_sel:DWORD dst_unused:UNUSED_PAD src0_sel:WORD_1 src1_sel:DWORD
	v_mfma_f32_16x16x4_f32 v[0:3], v35, v12, v[4:7]
	v_and_b32_sdwa v4, v23, v195 dst_sel:DWORD dst_unused:UNUSED_PAD src0_sel:WORD_1 src1_sel:DWORD
	v_and_b32_sdwa v5, v22, v195 dst_sel:DWORD dst_unused:UNUSED_PAD src0_sel:WORD_1 src1_sel:DWORD
	v_add3_u32 v4, v23, v4, s54
	v_add3_u32 v5, v22, v5, s54
	v_and_b32_e32 v12, 0xffff0000, v4
	v_and_b32_e32 v16, 0xffff0000, v5
	v_add3_u32 v9, v21, v9, s54
	v_mfma_f32_16x16x4_f32 v[4:7], v38, v15, 0
	v_or_b32_sdwa v15, v12, v9 dst_sel:DWORD dst_unused:UNUSED_PAD src0_sel:DWORD src1_sel:WORD_1
	v_or_b32_sdwa v14, v16, v14 dst_sel:DWORD dst_unused:UNUSED_PAD src0_sel:DWORD src1_sel:WORD_1
	global_store_dwordx2 v[40:41], v[14:15], off offset:2976 nt
	v_mov_b32_e32 v14, v0
	v_mov_b32_e32 v15, v2
	v_pk_mul_f32 v[14:15], v[42:43], v[14:15] op_sel_hi:[0,1]
	v_mov_b32_e32 v2, v1
	v_mfma_f32_16x16x4_f32 v[4:7], v39, v17, v[4:7]
	v_and_b32_sdwa v0, v15, v195 dst_sel:DWORD dst_unused:UNUSED_PAD src0_sel:WORD_1 src1_sel:DWORD
	v_and_b32_sdwa v1, v14, v195 dst_sel:DWORD dst_unused:UNUSED_PAD src0_sel:WORD_1 src1_sel:DWORD
	v_mul_f32_e64 v16, v42, v2
	v_mul_f32_e64 v17, v42, v3
	v_add3_u32 v9, v14, v1, s54
	v_add3_u32 v12, v15, v0, s54
	v_and_b32_sdwa v14, v17, v195 dst_sel:DWORD dst_unused:UNUSED_PAD src0_sel:WORD_1 src1_sel:DWORD
	v_and_b32_sdwa v15, v16, v195 dst_sel:DWORD dst_unused:UNUSED_PAD src0_sel:WORD_1 src1_sel:DWORD
	v_mfma_f32_16x16x4_f32 v[0:3], v34, v19, v[4:7]
	s_nop 0
	v_add3_u32 v4, v17, v14, s54
	v_add3_u32 v5, v16, v15, s54
	v_and_b32_e32 v4, 0xffff0000, v4
	v_and_b32_e32 v6, 0xffff0000, v5
	v_or_b32_sdwa v5, v4, v12 dst_sel:DWORD dst_unused:UNUSED_PAD src0_sel:DWORD src1_sel:WORD_1
	v_or_b32_sdwa v4, v6, v9 dst_sel:DWORD dst_unused:UNUSED_PAD src0_sel:DWORD src1_sel:WORD_1
	global_store_dwordx2 v[10:11], v[4:5], off offset:2976 nt
	v_mfma_f32_16x16x4_f32 v[0:3], v35, v13, v[0:3]
	s_nop 9
	v_mov_b32_e32 v4, v0
	v_mov_b32_e32 v5, v2
	v_pk_mul_f32 v[4:5], v[8:9], v[4:5] op_sel_hi:[0,1]
	v_mov_b32_e32 v2, v1
	v_pk_mul_f32 v[0:1], v[8:9], v[2:3] op_sel_hi:[0,1]
	v_and_b32_sdwa v2, v5, v195 dst_sel:DWORD dst_unused:UNUSED_PAD src0_sel:WORD_1 src1_sel:DWORD
	v_and_b32_sdwa v3, v4, v195 dst_sel:DWORD dst_unused:UNUSED_PAD src0_sel:WORD_1 src1_sel:DWORD
	v_add3_u32 v3, v4, v3, s54
	v_add3_u32 v2, v5, v2, s54
	v_and_b32_sdwa v4, v1, v195 dst_sel:DWORD dst_unused:UNUSED_PAD src0_sel:WORD_1 src1_sel:DWORD
	v_and_b32_sdwa v5, v0, v195 dst_sel:DWORD dst_unused:UNUSED_PAD src0_sel:WORD_1 src1_sel:DWORD
	v_add3_u32 v1, v1, v4, s54
	v_add3_u32 v0, v0, v5, s54
	v_and_b32_e32 v1, 0xffff0000, v1
	v_and_b32_e32 v0, 0xffff0000, v0
	v_or_b32_sdwa v1, v1, v2 dst_sel:DWORD dst_unused:UNUSED_PAD src0_sel:DWORD src1_sel:WORD_1
	v_or_b32_sdwa v0, v0, v3 dst_sel:DWORD dst_unused:UNUSED_PAD src0_sel:DWORD src1_sel:WORD_1
	global_store_dwordx2 v[24:25], v[0:1], off offset:2976 nt
	s_barrier
	s_cbranch_scc1 .LBB0_342

.LBB0_328:
	s_or_b64 exec, exec, s[12:13]
	s_load_dwordx2 s[24:25], s[18:19], 0xc8
	s_load_dwordx4 s[12:15], s[18:19], 0xe0
	s_waitcnt vmcnt(0)
	v_lshlrev_b32_e32 v110, 16, v80
	v_and_b32_e32 v111, 0xffff0000, v80
	v_lshlrev_b32_e32 v112, 16, v81
	v_and_b32_e32 v113, 0xffff0000, v81
	s_waitcnt lgkmcnt(0)
	global_load_dwordx4 v[84:87], v156, s[24:25]
	global_load_dwordx4 v[94:97], v156, s[12:13]
	s_load_dwordx2 s[20:21], s[18:19], 0xf0
	v_lshlrev_b32_e32 v114, 16, v82
	v_and_b32_e32 v115, 0xffff0000, v82
	v_lshlrev_b32_e32 v116, 16, v83
	v_and_b32_e32 v117, 0xffff0000, v83
	global_load_dwordx4 v[80:83], v156, s[14:15]
	s_waitcnt lgkmcnt(0)
	global_load_dwordx4 v[98:101], v156, s[20:21]
	v_lshlrev_b32_e32 v105, 16, v72
	v_and_b32_e32 v118, 0xffff0000, v72
	v_lshlrev_b32_e32 v119, 16, v73
	v_and_b32_e32 v120, 0xffff0000, v73
	v_lshlrev_b32_e32 v121, 16, v74
	v_and_b32_e32 v122, 0xffff0000, v74
	v_lshlrev_b32_e32 v123, 16, v75
	v_and_b32_e32 v124, 0xffff0000, v75
	global_load_dwordx4 v[72:75], v156, s[24:25] offset:16
	v_and_b32_e32 v89, 0xffff0000, v76
	v_lshlrev_b32_e32 v90, 16, v77
	v_and_b32_e32 v91, 0xffff0000, v77
	v_lshlrev_b32_e32 v104, 16, v76
	v_cndmask_b32_e64 v104, v104, v60, s[2:3]
	v_cndmask_b32_e64 v89, v89, v61, s[2:3]
	v_cndmask_b32_e64 v90, v90, v62, s[2:3]
	v_cndmask_b32_e64 v91, v91, v63, s[2:3]
	global_load_dwordx4 v[60:63], v156, s[14:15] offset:16
	v_lshlrev_b32_e32 v92, 16, v78
	v_and_b32_e32 v93, 0xffff0000, v78
	v_lshlrev_b32_e32 v102, 16, v79
	v_and_b32_e32 v103, 0xffff0000, v79
	v_and_b32_e32 v77, 0xffff0000, v36
	v_lshlrev_b32_e32 v76, 16, v36
	v_and_b32_e32 v36, 0xffff0000, v32
	v_lshlrev_b32_e32 v32, 16, v32
	v_and_b32_e32 v79, 0xffff0000, v37
	v_lshlrev_b32_e32 v78, 16, v37
	v_and_b32_e32 v37, 0xffff0000, v33
	v_lshlrev_b32_e32 v125, 16, v33
	v_cndmask_b32_e64 v92, v92, v64, s[2:3]
	v_cndmask_b32_e64 v93, v93, v65, s[2:3]
	v_cndmask_b32_e64 v102, v102, v66, s[2:3]
	v_cndmask_b32_e64 v103, v103, v67, s[2:3]
	v_cndmask_b32_e64 v33, v36, v69, s[2:3]
	v_cndmask_b32_e64 v32, v32, v68, s[2:3]
	v_cndmask_b32_e64 v37, v37, v71, s[2:3]
	v_cndmask_b32_e64 v36, v125, v70, s[2:3]
	global_load_dwordx4 v[64:67], v156, s[20:21] offset:16
	global_load_dwordx4 v[68:71], v156, s[12:13] offset:16
	v_pk_add_f32 v[32:33], v[32:33], v[76:77] neg_lo:[0,1] neg_hi:[0,1]
	v_sub_f32_e32 v102, v102, v116
	v_sub_f32_e32 v103, v103, v117
	v_pk_fma_f32 v[32:33], v[48:49], v[32:33], v[76:77]
	v_fmac_f32_e32 v116, v54, v102
	v_fmac_f32_e32 v117, v55, v103
	v_sub_f32_e32 v92, v92, v114
	v_sub_f32_e32 v93, v93, v115
	v_fmac_f32_e32 v114, v52, v92
	v_fmac_f32_e32 v115, v53, v93
	v_sub_f32_e32 v90, v90, v112
	v_sub_f32_e32 v91, v91, v113
	v_fmac_f32_e32 v112, v58, v90
	v_fmac_f32_e32 v113, v59, v91
	v_sub_f32_e32 v104, v104, v110
	v_sub_f32_e32 v89, v89, v111
	v_fmac_f32_e32 v110, v56, v104
	v_fmac_f32_e32 v111, v57, v89
	s_waitcnt vmcnt(7)
	v_add_f32_e32 v48, v84, v105
	v_add_f32_e32 v49, v85, v118
	v_mul_f32_e32 v54, 0xbfb8aa3b, v48
	v_mul_f32_e32 v55, 0xbfb8aa3b, v49
	v_exp_f32_e32 v54, v54
	v_exp_f32_e32 v55, v55
	v_add_f32_e32 v52, v86, v119
	v_add_f32_e32 v53, v87, v120
	v_mul_f32_e32 v52, 0xbfb8aa3b, v52
	v_mul_f32_e32 v53, 0xbfb8aa3b, v53
	v_exp_f32_e32 v52, v52
	v_exp_f32_e32 v53, v53
	v_add_f32_e32 v54, 1.0, v54
	v_add_f32_e32 v55, 1.0, v55
	v_rcp_f32_e32 v92, v54
	v_rcp_f32_e32 v93, v55
	v_add_f32_e32 v52, 1.0, v52
	v_add_f32_e32 v53, 1.0, v53
	s_waitcnt vmcnt(6)
	v_pk_mul_f32 v[90:91], v[32:33], v[94:95]
	v_rcp_f32_e32 v94, v52
	v_rcp_f32_e32 v95, v53
	v_pk_add_f32 v[52:53], v[92:93], -1.0 op_sel_hi:[1,0]
	v_pk_mul_f32 v[48:49], v[90:91], v[90:91]
	s_waitcnt vmcnt(5)
	v_pk_fma_f32 v[52:53], v[80:81], v[52:53], 1.0 op_sel_hi:[1,1,0]
	v_lshlrev_b32_e32 v118, 6, v109
	v_pk_mul_f32 v[80:81], v[32:33], v[52:53]
	s_nop 0
	v_mul_f32_e32 v32, v110, v80
	v_mul_f32_e32 v33, v111, v81
	s_waitcnt vmcnt(4)
	v_fma_f32 v52, v98, v32, 0
	v_fmac_f32_e32 v52, v99, v33
	v_pk_add_f32 v[32:33], v[36:37], v[78:79] neg_lo:[0,1] neg_hi:[0,1]
	v_pk_add_f32 v[36:37], v[94:95], -1.0 op_sel_hi:[1,0]
	v_pk_fma_f32 v[32:33], v[50:51], v[32:33], v[78:79]
	v_pk_fma_f32 v[36:37], v[82:83], v[36:37], 1.0 op_sel_hi:[1,1,0]
	s_waitcnt vmcnt(3)
	v_add_f32_e32 v50, v73, v122
	v_pk_mul_f32 v[82:83], v[32:33], v[36:37]
	v_add_f32_e32 v37, v72, v121
	v_mul_f32_e32 v37, 0xbfb8aa3b, v37
	v_exp_f32_e32 v37, v37
	v_mul_f32_e32 v50, 0xbfb8aa3b, v50
	v_exp_f32_e32 v50, v50
	v_mul_f32_e32 v36, v112, v82
	v_fmac_f32_e32 v52, v100, v36
	v_mul_f32_e32 v36, v113, v83
	v_fmac_f32_e32 v52, v101, v36
	v_add_f32_e32 v36, 1.0, v37
	v_rcp_f32_e32 v98, v36
	v_add_f32_e32 v36, 1.0, v50
	v_rcp_f32_e32 v99, v36
	v_and_b32_e32 v37, 0xffff0000, v38
	v_lshlrev_b32_e32 v36, 16, v38
	v_and_b32_e32 v38, 0xffff0000, v34
	v_lshlrev_b32_e32 v34, 16, v34
	v_cndmask_b32_e64 v45, v38, v45, s[2:3]
	v_cndmask_b32_e64 v44, v34, v44, s[2:3]
	v_pk_add_f32 v[44:45], v[44:45], v[36:37] neg_lo:[0,1] neg_hi:[0,1]
	v_add_f32_e32 v38, v74, v123
	v_pk_fma_f32 v[36:37], v[40:41], v[44:45], v[36:37]
	v_pk_add_f32 v[40:41], v[98:99], -1.0 op_sel_hi:[1,0]
	v_mul_f32_e32 v38, 0xbfb8aa3b, v38
	s_waitcnt vmcnt(2)
	v_pk_fma_f32 v[40:41], v[60:61], v[40:41], 1.0 op_sel_hi:[1,1,0]
	v_exp_f32_e32 v38, v38
	v_pk_mul_f32 v[84:85], v[36:37], v[40:41]
	v_add_f32_e32 v40, v75, v124
	v_mul_f32_e32 v40, 0xbfb8aa3b, v40
	v_exp_f32_e32 v40, v40
	v_mul_f32_e32 v34, v114, v84
	s_waitcnt vmcnt(1)
	v_fmac_f32_e32 v52, v64, v34
	v_mul_f32_e32 v34, v115, v85
	v_fmac_f32_e32 v52, v65, v34
	v_add_f32_e32 v34, 1.0, v38
	v_rcp_f32_e32 v102, v34
	v_add_f32_e32 v34, 1.0, v40
	v_rcp_f32_e32 v103, v34
	v_and_b32_e32 v34, 0xffff0000, v35
	v_lshlrev_b32_e32 v38, 16, v35
	v_and_b32_e32 v41, 0xffff0000, v39
	v_lshlrev_b32_e32 v40, 16, v39
	v_cndmask_b32_e64 v35, v34, v47, s[2:3]
	v_cndmask_b32_e64 v34, v38, v46, s[2:3]
	v_pk_add_f32 v[34:35], v[34:35], v[40:41] neg_lo:[0,1] neg_hi:[0,1]
	v_pk_add_f32 v[38:39], v[102:103], -1.0 op_sel_hi:[1,0]
	v_pk_fma_f32 v[34:35], v[42:43], v[34:35], v[40:41]
	v_pk_fma_f32 v[38:39], v[62:63], v[38:39], 1.0 op_sel_hi:[1,1,0]
	v_pk_mul_f32 v[96:97], v[32:33], v[96:97]
	v_pk_mul_f32 v[86:87], v[34:35], v[38:39]
	v_pk_mul_f32 v[32:33], v[96:97], v[96:97]
	v_mul_f32_e32 v38, v116, v86
	v_fmac_f32_e32 v52, v66, v38
	v_add_f32_e32 v38, v48, v49
	s_waitcnt vmcnt(0)
	v_pk_mul_f32 v[100:101], v[36:37], v[68:69]
	v_add_f32_e32 v32, v32, v38
	v_pk_mul_f32 v[36:37], v[100:101], v[100:101]
	v_add_f32_e32 v32, v33, v32
	v_pk_mul_f32 v[104:105], v[34:35], v[70:71]
	v_add_f32_e32 v32, v32, v36
	v_pk_mul_f32 v[34:35], v[104:105], v[104:105]
	v_add_f32_e32 v32, v37, v32
	v_add_f32_e32 v32, v34, v32
	v_add_f32_e32 v32, v35, v32
	v_mul_f32_e32 v33, v117, v87
	v_fmac_f32_e32 v52, v67, v33
	v_add_f32_dpp v32, v32, v32 quad_perm:[1,0,3,2] row_mask:0xf bank_mask:0xf bound_ctrl:1
	s_nop 1
	v_add_f32_dpp v89, v32, v32 quad_perm:[2,3,0,1] row_mask:0xf bank_mask:0xf bound_ctrl:1
	v_add_f32_dpp v32, v52, v52 quad_perm:[1,0,3,2] row_mask:0xf bank_mask:0xf bound_ctrl:1
	s_nop 0
	v_mov_b32_dpp v119, v89 row_half_mirror row_mask:0xf bank_mask:0xf bound_ctrl:1
	v_add_f32_dpp v120, v32, v32 quad_perm:[2,3,0,1] row_mask:0xf bank_mask:0xf bound_ctrl:1
	s_nop 1
	v_mov_b32_dpp v121, v120 row_half_mirror row_mask:0xf bank_mask:0xf bound_ctrl:1
	s_and_saveexec_b64 s[12:13], s[4:5]
	s_xor_b64 s[4:5], exec, s[12:13]
	v_lshlrev_b32_e32 v118, 6, v109
	s_or_saveexec_b64 s[12:13], s[4:5]
	s_ashr_i32 s7, s6, 31
	v_mov_b32_e32 v55, 1.0
	v_mov_b32_e32 v63, 0
	v_lshlrev_b32_e32 v88, 2, v88
	v_mov_b32_e32 v62, 0
	v_mov_b32_e32 v61, 0
	v_mov_b32_e32 v60, 0
	v_mov_b32_e32 v67, 0
	v_mov_b32_e32 v66, 0
	v_mov_b32_e32 v65, 0
	v_mov_b32_e32 v64, 0
	v_mov_b32_e32 v59, 0
	v_mov_b32_e32 v58, 0
	v_mov_b32_e32 v57, 0
	v_mov_b32_e32 v56, 0
	v_mov_b32_e32 v75, 0
	v_mov_b32_e32 v74, 0
	v_mov_b32_e32 v73, 0
	v_mov_b32_e32 v72, 0
	v_mov_b32_e32 v54, 1.0
	v_mov_b32_e32 v53, 1.0
	v_mov_b32_e32 v52, 1.0
	v_mov_b32_e32 v48, 1.0
	v_mov_b32_e32 v49, 1.0
	v_mov_b32_e32 v50, 1.0
	v_mov_b32_e32 v51, 1.0
	v_mov_b32_e32 v70, 0
	v_mov_b32_e32 v71, 0
	v_mov_b32_e32 v68, 0
	v_mov_b32_e32 v69, 0
	v_mov_b32_e32 v78, 0
	v_mov_b32_e32 v79, 0
	v_mov_b32_e32 v76, 0
	v_mov_b32_e32 v77, 0
	v_mov_b32_e32 v34, 0
	v_mov_b32_e32 v35, 0
	v_mov_b32_e32 v32, 0
	v_mov_b32_e32 v33, 0
	v_mov_b32_e32 v42, 0
	v_mov_b32_e32 v43, 0
	v_mov_b32_e32 v40, 0
	v_mov_b32_e32 v41, 0
	v_mov_b32_e32 v38, 0
	v_mov_b32_e32 v39, 0
	v_mov_b32_e32 v36, 0
	v_mov_b32_e32 v37, 0
	v_mov_b32_e32 v46, 0
	v_mov_b32_e32 v47, 0
	v_mov_b32_e32 v44, 0
	v_mov_b32_e32 v45, 0
	s_xor_b64 exec, exec, s[12:13]
	s_cbranch_execz .LBB0_332
	s_load_dwordx2 s[4:5], s[18:19], 0xb8
	v_add_f32_e32 v32, v89, v119
	s_mov_b32 s1, 0xf800000
	v_mul_f32_e32 v33, 0x4f800000, v32
	v_cmp_gt_f32_e32 vcc, s1, v32
	s_waitcnt lgkmcnt(0)
	global_load_dwordx4 v[48:51], v156, s[4:5] offset:16
	global_load_dwordx4 v[52:55], v156, s[4:5]
	v_cndmask_b32_e32 v32, v32, v33, vcc
	v_sqrt_f32_e32 v33, v32
	v_and_b32_e32 v57, 0xffff0000, v11
	v_lshlrev_b32_e32 v66, 16, v11
	v_and_b32_e32 v67, 0xffff0000, v10
	v_add_u32_e32 v11, -1, v33
	v_add_u32_e32 v34, 1, v33
	v_fma_f32 v35, -v11, v33, v32
	v_fma_f32 v36, -v34, v33, v32
	v_cmp_ge_f32_e64 s[4:5], 0, v35
	v_lshlrev_b32_e32 v68, 16, v10
	v_and_b32_e32 v64, 0xffff0000, v31
	v_cndmask_b32_e64 v11, v33, v11, s[4:5]
	v_cmp_lt_f32_e64 s[4:5], 0, v36
	v_lshlrev_b32_e32 v65, 16, v31
	v_and_b32_e32 v60, 0xffff0000, v30
	v_cndmask_b32_e64 v11, v11, v34, s[4:5]
	v_mul_f32_e32 v33, 0x37800000, v11
	v_cndmask_b32_e32 v11, v11, v33, vcc
	v_cmp_class_f32_e32 vcc, v32, v196
	v_lshlrev_b32_e32 v61, 16, v30
	v_and_b32_e32 v31, 0xffff0000, v25
	v_cndmask_b32_e32 v11, v11, v32, vcc
	v_max_f32_e32 v11, 0x2b8cbccc, v11
	v_div_scale_f32 v32, s[4:5], v11, v11, 1.0
	v_rcp_f32_e32 v33, v32
	v_div_scale_f32 v10, vcc, 1.0, v11, 1.0
	v_lshlrev_b32_e32 v30, 16, v25
	v_fma_f32 v34, -v32, v33, 1.0
	v_fmac_f32_e32 v33, v34, v33
	v_mul_f32_e32 v34, v10, v33
	v_fma_f32 v35, -v32, v34, v10
	v_fmac_f32_e32 v34, v35, v33
	v_fma_f32 v10, -v32, v34, v10
	v_div_fmas_f32 v10, v10, v33, v34
	v_div_fixup_f32 v10, v10, v11, 1.0
	v_pk_mul_f32 v[32:33], v[104:105], v[10:11] op_sel_hi:[1,0]
	v_pk_mul_f32 v[40:41], v[100:101], v[10:11] op_sel_hi:[1,0]
	v_pk_mul_f32 v[42:43], v[96:97], v[10:11] op_sel_hi:[1,0]
	v_pk_mul_f32 v[10:11], v[90:91], v[10:11] op_sel_hi:[1,0]
	v_pk_mul_f32 v[38:39], v[102:103], v[32:33]
	v_pk_add_f32 v[34:35], v[32:33], 0 neg_lo:[1,1] neg_hi:[1,1]
	v_pk_mul_f32 v[36:37], v[98:99], v[40:41]
	v_pk_add_f32 v[32:33], v[40:41], 0 neg_lo:[1,1] neg_hi:[1,1]
	v_pk_mul_f32 v[44:45], v[92:93], v[10:11]
	v_pk_add_f32 v[40:41], v[10:11], 0 neg_lo:[1,1] neg_hi:[1,1]
	v_and_b32_e32 v25, 0xffff0000, v28
	v_lshlrev_b32_e32 v56, 16, v28
	v_and_b32_e32 v58, 0xffff0000, v29
	v_lshlrev_b32_e32 v59, 16, v29
	v_and_b32_e32 v29, 0xffff0000, v24
	v_lshlrev_b32_e32 v28, 16, v24
	v_add_f32_e32 v24, v120, v121
	v_and_b32_e32 v63, 0xffff0000, v27
	v_lshlrev_b32_e32 v62, 16, v27
	v_and_b32_e32 v27, 0xffff0000, v26
	v_lshlrev_b32_e32 v26, 16, v26
	v_lshlrev_b32_e32 v156, 8, v109
	v_mov_b32_e32 v89, v157
	v_pk_mul_f32 v[46:47], v[94:95], v[42:43]
	v_pk_add_f32 v[42:43], v[42:43], 0 neg_lo:[1,1] neg_hi:[1,1]
	v_mov_b32_e32 v75, v113
	v_mov_b32_e32 v74, v112
	v_mov_b32_e32 v73, v111
	v_mov_b32_e32 v72, v110
	v_mov_b32_e32 v70, v86
	v_mov_b32_e32 v71, v87
	v_mov_b32_e32 v69, v85
	v_mov_b32_e32 v78, v82
	v_mov_b32_e32 v79, v83
	v_mov_b32_e32 v76, v80
	v_mov_b32_e32 v77, v81
	s_waitcnt vmcnt(1)
	v_add_f32_e32 v10, v51, v57
	v_add_f32_e32 v11, v50, v66
	v_mul_f32_e32 v50, 0xbfb8aa3b, v10
	v_exp_f32_e32 v50, v50
	v_mul_f32_e32 v51, 0xbfb8aa3b, v11
	v_add_f32_e32 v49, v49, v67
	v_exp_f32_e32 v51, v51
	v_add_f32_e32 v50, 1.0, v50
	v_log_f32_e32 v50, v50
	v_mul_f32_e32 v57, 0xbfb8aa3b, v49
	v_cmp_gt_f32_e32 vcc, s95, v10
	v_exp_f32_e32 v57, v57
	v_mul_f32_e32 v50, 0x3f317218, v50
	v_cndmask_b32_e64 v10, v50, -v10, vcc
	v_sub_f32_e32 v10, -0.5, v10
	v_add_f32_e32 v48, v48, v68
	v_add_f32_e32 v51, 1.0, v51
	v_mul_f32_e32 v10, 0x3fb8aa3b, v10
	v_mul_f32_e32 v66, 0xbfb8aa3b, v48
	v_log_f32_e32 v51, v51
	v_exp_f32_e32 v10, v10
	v_add_f32_e32 v57, 1.0, v57
	v_exp_f32_e32 v66, v66
	v_log_f32_e32 v57, v57
	v_mul_f32_e32 v51, 0x3f317218, v51
	v_cmp_gt_f32_e32 vcc, s95, v11
	v_mul_f32_e32 v10, 0xbfb8aa3b, v10
	v_mul_f32_e32 v57, 0x3f317218, v57
	v_cndmask_b32_e64 v11, v51, -v11, vcc
	v_exp_f32_e32 v51, v10
	v_add_f32_e32 v10, 1.0, v66
	v_cmp_gt_f32_e32 vcc, s95, v49
	v_log_f32_e32 v10, v10
	v_sub_f32_e32 v11, -0.5, v11
	v_cndmask_b32_e64 v49, v57, -v49, vcc
	v_sub_f32_e32 v49, -0.5, v49
	v_mul_f32_e32 v11, 0x3fb8aa3b, v11
	v_mul_f32_e32 v49, 0x3fb8aa3b, v49
	v_exp_f32_e32 v11, v11
	v_exp_f32_e32 v49, v49
	v_mul_f32_e32 v10, 0x3f317218, v10
	v_cmp_gt_f32_e32 vcc, s95, v48
	v_mul_f32_e32 v11, 0xbfb8aa3b, v11
	v_exp_f32_e32 v50, v11
	v_cndmask_b32_e64 v10, v10, -v48, vcc
	v_sub_f32_e32 v10, -0.5, v10
	v_and_b32_e32 v48, 0xffff0000, v9
	v_mul_f32_e32 v10, 0x3fb8aa3b, v10
	s_waitcnt vmcnt(0)
	v_add_f32_e32 v55, v55, v48
	v_lshlrev_b32_e32 v9, 16, v9
	v_mul_f32_e32 v11, 0xbfb8aa3b, v49
	v_exp_f32_e32 v10, v10
	v_mul_f32_e32 v48, 0xbfb8aa3b, v55
	v_add_f32_e32 v9, v54, v9
	v_exp_f32_e32 v57, v48
	v_exp_f32_e32 v49, v11
	v_mul_f32_e32 v11, 0xbfb8aa3b, v9
	v_exp_f32_e32 v11, v11
	v_mul_f32_e32 v10, 0xbfb8aa3b, v10
	v_exp_f32_e32 v48, v10
	v_add_f32_e32 v10, 1.0, v57
	v_log_f32_e32 v10, v10
	v_add_f32_e32 v11, 1.0, v11
	v_log_f32_e32 v11, v11
	v_cmp_gt_f32_e32 vcc, s95, v55
	v_mul_f32_e32 v10, 0x3f317218, v10
	v_mov_b32_e32 v67, v117
	v_cndmask_b32_e64 v10, v10, -v55, vcc
	v_mul_f32_e32 v11, 0x3f317218, v11
	v_cmp_gt_f32_e32 vcc, s95, v9
	v_sub_f32_e32 v10, -0.5, v10
	v_mul_f32_e32 v10, 0x3fb8aa3b, v10
	v_cndmask_b32_e64 v9, v11, -v9, vcc
	v_and_b32_e32 v11, 0xffff0000, v8
	v_add_f32_e32 v11, v53, v11
	v_exp_f32_e32 v10, v10
	v_mul_f32_e32 v53, 0xbfb8aa3b, v11
	v_exp_f32_e32 v53, v53
	v_lshlrev_b32_e32 v8, 16, v8
	v_mul_f32_e32 v10, 0xbfb8aa3b, v10
	v_exp_f32_e32 v55, v10
	v_add_f32_e32 v10, 1.0, v53
	v_add_f32_e32 v8, v52, v8
	v_log_f32_e32 v10, v10
	v_mul_f32_e32 v52, 0xbfb8aa3b, v8
	v_exp_f32_e32 v52, v52
	v_cmp_gt_f32_e32 vcc, s95, v11
	v_mul_f32_e32 v10, 0x3f317218, v10
	v_sub_f32_e32 v9, -0.5, v9
	v_cndmask_b32_e64 v10, v10, -v11, vcc
	v_add_f32_e32 v11, 1.0, v52
	v_log_f32_e32 v11, v11
	v_cmp_gt_f32_e32 vcc, s95, v8
	v_mul_f32_e32 v9, 0x3fb8aa3b, v9
	v_sub_f32_e32 v10, -0.5, v10
	v_mul_f32_e32 v11, 0x3f317218, v11
	v_cndmask_b32_e64 v8, v11, -v8, vcc
	v_sub_f32_e32 v8, -0.5, v8
	v_exp_f32_e32 v9, v9
	v_mul_f32_e32 v10, 0x3fb8aa3b, v10
	v_mul_f32_e32 v8, 0x3fb8aa3b, v8
	v_exp_f32_e32 v10, v10
	v_exp_f32_e32 v8, v8
	v_mul_f32_e32 v9, 0xbfb8aa3b, v9
	v_exp_f32_e32 v54, v9
	v_mul_f32_e32 v9, 0xbfb8aa3b, v10
	v_mul_f32_e32 v8, 0xbfb8aa3b, v8
	v_exp_f32_e32 v53, v9
	v_exp_f32_e32 v52, v8
	v_cndmask_b32_e64 v9, v25, v21, s[2:3]
	v_cndmask_b32_e64 v8, v56, v20, s[2:3]
	v_pk_add_f32 v[8:9], v[8:9], v[28:29] neg_lo:[0,1] neg_hi:[0,1]
	v_mov_b32_e32 v66, v116
	v_pk_fma_f32 v[56:57], v[12:13], v[8:9], v[28:29]
	v_mov_b32_e32 v68, v84
	v_pk_mul_f32 v[8:9], v[56:57], v[24:25] op_sel_hi:[1,0]
	s_nop 0
	v_and_b32_sdwa v10, v9, v195 dst_sel:DWORD dst_unused:UNUSED_PAD src0_sel:WORD_1 src1_sel:DWORD
	v_and_b32_sdwa v11, v8, v195 dst_sel:DWORD dst_unused:UNUSED_PAD src0_sel:WORD_1 src1_sel:DWORD
	v_add3_u32 v9, v9, v10, s54
	v_add3_u32 v8, v8, v11, s54
	v_cndmask_b32_e64 v11, v58, v23, s[2:3]
	v_cndmask_b32_e64 v10, v59, v22, s[2:3]
	v_pk_add_f32 v[10:11], v[10:11], v[30:31] neg_lo:[0,1] neg_hi:[0,1]
	v_and_b32_e32 v9, 0xffff0000, v9
	v_pk_fma_f32 v[58:59], v[14:15], v[10:11], v[30:31]
	v_and_b32_e32 v8, 0xffff0000, v8
	v_pk_mul_f32 v[10:11], v[58:59], v[24:25] op_sel_hi:[1,0]
	v_or_b32_sdwa v9, v9, v0 dst_sel:DWORD dst_unused:UNUSED_PAD src0_sel:DWORD src1_sel:WORD_1
	v_or_b32_sdwa v8, v8, v0 dst_sel:DWORD dst_unused:UNUSED_PAD src0_sel:DWORD src1_sel:WORD_0
	v_and_b32_sdwa v0, v11, v195 dst_sel:DWORD dst_unused:UNUSED_PAD src0_sel:WORD_1 src1_sel:DWORD
	v_and_b32_sdwa v12, v10, v195 dst_sel:DWORD dst_unused:UNUSED_PAD src0_sel:WORD_1 src1_sel:DWORD
	v_add3_u32 v0, v11, v0, s54
	v_add3_u32 v10, v10, v12, s54
	v_and_b32_e32 v0, 0xffff0000, v0
	v_and_b32_e32 v10, 0xffff0000, v10
	v_or_b32_sdwa v11, v0, v1 dst_sel:DWORD dst_unused:UNUSED_PAD src0_sel:DWORD src1_sel:WORD_1
	v_or_b32_sdwa v10, v10, v1 dst_sel:DWORD dst_unused:UNUSED_PAD src0_sel:DWORD src1_sel:WORD_0
	v_cndmask_b32_e64 v1, v60, v17, s[2:3]
	v_cndmask_b32_e64 v0, v61, v16, s[2:3]
	v_pk_add_f32 v[0:1], v[0:1], v[26:27] neg_lo:[0,1] neg_hi:[0,1]
	s_nop 0
	v_pk_fma_f32 v[60:61], v[4:5], v[0:1], v[26:27]
	s_nop 0
	v_pk_mul_f32 v[0:1], v[60:61], v[24:25] op_sel_hi:[1,0]
	s_nop 0
	v_and_b32_sdwa v4, v1, v195 dst_sel:DWORD dst_unused:UNUSED_PAD src0_sel:WORD_1 src1_sel:DWORD
	v_and_b32_sdwa v5, v0, v195 dst_sel:DWORD dst_unused:UNUSED_PAD src0_sel:WORD_1 src1_sel:DWORD
	v_add3_u32 v1, v1, v4, s54
	v_add3_u32 v0, v0, v5, s54
	v_and_b32_e32 v1, 0xffff0000, v1
	v_and_b32_e32 v0, 0xffff0000, v0
	v_or_b32_sdwa v5, v1, v2 dst_sel:DWORD dst_unused:UNUSED_PAD src0_sel:DWORD src1_sel:WORD_1
	v_or_b32_sdwa v4, v0, v2 dst_sel:DWORD dst_unused:UNUSED_PAD src0_sel:DWORD src1_sel:WORD_0
	v_cndmask_b32_e64 v1, v64, v19, s[2:3]
	v_cndmask_b32_e64 v0, v65, v18, s[2:3]
	v_pk_add_f32 v[0:1], v[0:1], v[62:63] neg_lo:[0,1] neg_hi:[0,1]
	s_lshl_b64 s[2:3], s[6:7], 12
	v_pk_fma_f32 v[62:63], v[6:7], v[0:1], v[62:63]
	s_add_u32 s2, s16, s2
	v_pk_mul_f32 v[0:1], v[62:63], v[24:25] op_sel_hi:[1,0]
	s_addc_u32 s3, s17, s3
	v_and_b32_sdwa v2, v1, v195 dst_sel:DWORD dst_unused:UNUSED_PAD src0_sel:WORD_1 src1_sel:DWORD
	v_and_b32_sdwa v6, v0, v195 dst_sel:DWORD dst_unused:UNUSED_PAD src0_sel:WORD_1 src1_sel:DWORD
	v_add3_u32 v1, v1, v2, s54
	v_add3_u32 v0, v0, v6, s54
	v_and_b32_e32 v1, 0xffff0000, v1
	v_and_b32_e32 v0, 0xffff0000, v0
	v_or_b32_sdwa v7, v1, v3 dst_sel:DWORD dst_unused:UNUSED_PAD src0_sel:DWORD src1_sel:WORD_1
	v_or_b32_sdwa v6, v0, v3 dst_sel:DWORD dst_unused:UNUSED_PAD src0_sel:DWORD src1_sel:WORD_0
	v_lshl_add_u64 v[0:1], s[2:3], 0, v[156:157]
	v_lshl_add_u64 v[0:1], v[0:1], 0, v[88:89]
	s_mov_b64 s[2:3], 0x34800000
	v_lshl_add_u64 v[2:3], v[0:1], 0, s[2:3]
	v_add_co_u32_e32 v0, vcc, s96, v0
	v_mov_b32_e32 v65, v115
	s_nop 0
	v_addc_co_u32_e32 v1, vcc, 0, v1, vcc
	v_mov_b32_e32 v64, v114
	global_store_dwordx4 v[0:1], v[8:11], off nt
	global_store_dwordx4 v[2:3], v[4:7], off offset:16 nt
.LBB0_332:
	s_or_b64 exec, exec, s[12:13]
	s_mul_i32 s0, s0, 0x8800
	s_add_i32 s16, s0, 0
	s_mul_i32 s1, s6, 0x4800
	s_mul_hi_i32 s0, s6, 0x4800
	s_add_u32 s1, s10, s1
	s_addc_u32 s0, s11, s0
	v_mul_u32_u24_e32 v0, 0x44, v109
	s_add_u32 s12, s1, 0x2a600000
	v_and_b32_e32 v16, 0x7f, v108
	v_lshlrev_b32_e32 v0, 2, v0
	s_addc_u32 s13, s0, 0
	v_add3_u32 v0, s16, v0, v88
	v_lshlrev_b32_e32 v1, 2, v118
	v_cmp_gt_u32_e32 vcc, 64, v16
	v_add3_u32 v1, s16, v1, v88
	ds_write_b128 v0, v[72:75]
	ds_write_b128 v1, v[52:55] offset:17408
	ds_write_b128 v0, v[76:79] offset:4352
	ds_write_b128 v0, v[40:43] offset:8704
	ds_write_b128 v0, v[44:47] offset:13056
	ds_write_b128 v1, v[56:59] offset:28160
	ds_write_b128 v0, v[64:67] offset:16
	ds_write_b128 v1, v[48:51] offset:17424
	ds_write_b128 v0, v[68:71] offset:4368
	ds_write_b128 v0, v[32:35] offset:8720
	ds_write_b128 v0, v[36:39] offset:13072
	ds_write_b128 v1, v[60:63] offset:28176
	s_waitcnt lgkmcnt(0)
	s_barrier
	s_and_saveexec_b64 s[2:3], vcc
	s_cbranch_execz .LBB0_334
	v_lshlrev_b32_e32 v156, 2, v16
	v_add_u32_e32 v4, s16, v156
	v_add_u32_e32 v0, 0x4200, v4
	ds_read2_b32 v[0:1], v0 offset0:60 offset1:128
	v_add_u32_e32 v5, 0x3000, v4
	v_add_u32_e32 v17, 0x1000, v4
	ds_read2_b32 v[2:3], v5 offset0:124 offset1:192
	v_add_u32_e32 v27, 0x2200, v4
	s_waitcnt lgkmcnt(1)
	v_div_scale_f32 v6, s[0:1], v1, v1, 1.0
	v_rcp_f32_e32 v7, v6
	v_div_scale_f32 v8, vcc, 1.0, v1, 1.0
	v_add_u32_e32 v28, 0x3400, v4
	v_fma_f32 v9, -v6, v7, 1.0
	v_fmac_f32_e32 v7, v9, v7
	v_mul_f32_e32 v9, v8, v7
	v_fma_f32 v10, -v6, v9, v8
	v_fmac_f32_e32 v9, v10, v7
	v_fma_f32 v6, -v6, v9, v8
	v_div_fmas_f32 v6, v6, v7, v9
	v_div_fixup_f32 v20, v6, v1, 1.0
	ds_read2_b32 v[6:7], v17 offset0:64 offset1:132
	ds_read2st64_b32 v[8:9], v4 offset0:69 offset1:70
	ds_read2_b32 v[10:11], v4 offset1:68
	ds_read2st64_b32 v[12:13], v4 offset0:71 offset1:72
	ds_read2st64_b32 v[14:15], v4 offset0:73 offset1:74
	ds_read2st64_b32 v[18:19], v4 offset0:75 offset1:76
	s_waitcnt lgkmcnt(4)
	v_mul_f32_e32 v8, v1, v8
	v_div_scale_f32 v21, s[0:1], v8, v8, 1.0
	v_rcp_f32_e32 v24, v21
	v_mul_f32_e32 v3, v20, v3
	v_mul_f32_e32 v6, v20, v6
	s_waitcnt lgkmcnt(3)
	v_mul_f32_e32 v10, v1, v10
	v_fma_f32 v20, -v21, v24, 1.0
	v_fmac_f32_e32 v24, v20, v24
	v_div_scale_f32 v20, vcc, 1.0, v8, 1.0
	v_mul_f32_e32 v25, v20, v24
	v_fma_f32 v22, -v21, v25, v20
	v_fmac_f32_e32 v25, v22, v24
	v_fma_f32 v26, -v21, v25, v20
	ds_read2_b32 v[20:21], v27 offset0:68 offset1:136
	ds_read2_b32 v[22:23], v28 offset0:4 offset1:72
	v_div_fmas_f32 v24, v26, v24, v25
	v_div_fixup_f32 v24, v24, v8, 1.0
	v_mul_f32_e32 v7, v24, v7
	s_waitcnt lgkmcnt(1)
	v_mul_f32_e32 v1, v1, v20
	s_waitcnt lgkmcnt(0)
	v_mul_f32_e32 v20, v24, v22
	v_mul_f32_e32 v22, v8, v9
	v_div_scale_f32 v9, s[0:1], v22, v22, 1.0
	v_rcp_f32_e32 v24, v9
	ds_write2_b32 v17, v6, v7 offset0:64 offset1:132
	v_mul_f32_e32 v6, v8, v11
	ds_write2_b32 v4, v10, v6 offset1:68
	v_fma_f32 v6, -v9, v24, 1.0
	v_fmac_f32_e32 v24, v6, v24
	v_div_scale_f32 v6, vcc, 1.0, v22, 1.0
	v_mul_f32_e32 v7, v6, v24
	v_fma_f32 v10, -v9, v7, v6
	v_fmac_f32_e32 v7, v10, v24
	v_fma_f32 v6, -v9, v7, v6
	v_div_fmas_f32 v6, v6, v24, v7
	v_div_fixup_f32 v10, v6, v22, 1.0
	v_mul_f32_e32 v6, v8, v21
	ds_write2_b32 v27, v1, v6 offset0:68 offset1:136
	v_add_u32_e32 v17, 0x1200, v4
	v_mul_f32_e32 v12, v22, v12
	ds_read2_b32 v[6:7], v17 offset0:72 offset1:140
	ds_read2_b32 v[8:9], v4 offset0:136 offset1:204
	v_div_scale_f32 v11, s[0:1], v12, v12, 1.0
	v_mul_f32_e32 v1, v10, v23
	v_rcp_f32_e32 v23, v11
	ds_write2_b32 v28, v20, v1 offset0:4 offset1:72
	s_waitcnt lgkmcnt(2)
	v_mul_f32_e32 v1, v10, v6
	s_waitcnt lgkmcnt(1)
	v_mul_f32_e32 v6, v22, v8
	v_fma_f32 v8, -v11, v23, 1.0
	v_fmac_f32_e32 v23, v8, v23
	v_div_scale_f32 v8, vcc, 1.0, v12, 1.0
	v_mul_f32_e32 v24, v8, v23
	v_fma_f32 v10, -v11, v24, v8
	v_fmac_f32_e32 v24, v10, v23
	v_add_u32_e32 v25, 0x2400, v4
	v_fma_f32 v8, -v11, v24, v8
	ds_read2_b32 v[10:11], v25 offset0:76 offset1:144
	ds_read2_b32 v[20:21], v28 offset0:140 offset1:208
	v_div_fmas_f32 v8, v8, v23, v24
	v_div_fixup_f32 v8, v8, v12, 1.0
	v_mul_f32_e32 v7, v8, v7
	s_waitcnt lgkmcnt(1)
	v_mul_f32_e32 v10, v22, v10
	v_mul_f32_e32 v22, v12, v13
	s_waitcnt lgkmcnt(0)
	v_mul_f32_e32 v20, v8, v20
	v_div_scale_f32 v8, s[0:1], v22, v22, 1.0
	v_rcp_f32_e32 v13, v8
	ds_write2_b32 v17, v1, v7 offset0:72 offset1:140
	v_mul_f32_e32 v1, v12, v9
	ds_write2_b32 v4, v6, v1 offset0:136 offset1:204
	v_fma_f32 v1, -v8, v13, 1.0
	v_fmac_f32_e32 v13, v1, v13
	v_div_scale_f32 v1, vcc, 1.0, v22, 1.0
	v_mul_f32_e32 v6, v1, v13
	v_fma_f32 v7, -v8, v6, v1
	v_fmac_f32_e32 v6, v7, v13
	v_fma_f32 v1, -v8, v6, v1
	v_div_fmas_f32 v1, v1, v13, v6
	v_div_fixup_f32 v1, v1, v22, 1.0
	v_mul_f32_e32 v6, v12, v11
	ds_write2_b32 v25, v10, v6 offset0:76 offset1:144
	v_mul_f32_e32 v10, v1, v21
	v_add_u32_e32 v17, 0x1400, v4
	v_add_u32_e32 v21, 0x400, v4
	v_mul_f32_e32 v14, v22, v14
	ds_read2_b32 v[6:7], v17 offset0:80 offset1:148
	ds_read2_b32 v[8:9], v21 offset0:16 offset1:84
	v_div_scale_f32 v11, s[0:1], v14, v14, 1.0
	v_rcp_f32_e32 v23, v11
	s_waitcnt lgkmcnt(1)
	v_mul_f32_e32 v1, v1, v6
	s_waitcnt lgkmcnt(0)
	v_mul_f32_e32 v6, v22, v8
	ds_write2_b32 v28, v20, v10 offset0:140 offset1:208
	v_fma_f32 v8, -v11, v23, 1.0
	v_fmac_f32_e32 v23, v8, v23
	v_div_scale_f32 v8, vcc, 1.0, v14, 1.0
	v_mul_f32_e32 v20, v8, v23
	v_add_u32_e32 v25, 0x3800, v4
	v_fma_f32 v10, -v11, v20, v8
	ds_read2_b32 v[12:13], v25 offset0:20 offset1:88
	v_fmac_f32_e32 v20, v10, v23
	v_fma_f32 v8, -v11, v20, v8
	v_div_fmas_f32 v8, v8, v23, v20
	v_div_fixup_f32 v8, v8, v14, 1.0
	v_mul_f32_e32 v15, v14, v15
	s_waitcnt lgkmcnt(0)
	v_mul_f32_e32 v12, v8, v12
	v_mul_f32_e32 v7, v8, v7
	v_div_scale_f32 v8, s[0:1], v15, v15, 1.0
	v_rcp_f32_e32 v20, v8
	ds_write2_b32 v17, v1, v7 offset0:80 offset1:148
	v_mul_f32_e32 v1, v14, v9
	v_add_u32_e32 v24, 0x2600, v4
	ds_write2_b32 v21, v6, v1 offset0:16 offset1:84
	v_fma_f32 v1, -v8, v20, 1.0
	ds_read2_b32 v[10:11], v24 offset0:84 offset1:152
	v_fmac_f32_e32 v20, v1, v20
	v_div_scale_f32 v1, vcc, 1.0, v15, 1.0
	v_mul_f32_e32 v6, v1, v20
	v_fma_f32 v7, -v8, v6, v1
	v_fmac_f32_e32 v6, v7, v20
	v_fma_f32 v1, -v8, v6, v1
	s_waitcnt lgkmcnt(0)
	v_mul_f32_e32 v10, v22, v10
	v_div_fmas_f32 v1, v1, v20, v6
	v_mul_f32_e32 v6, v14, v11
	ds_write2_b32 v24, v10, v6 offset0:84 offset1:152
	v_add_u32_e32 v14, 0x1600, v4
	v_mul_f32_e32 v17, v15, v18
	ds_read2_b32 v[6:7], v14 offset0:88 offset1:156
	ds_read2_b32 v[8:9], v21 offset0:152 offset1:220
	v_div_scale_f32 v11, s[0:1], v17, v17, 1.0
	v_rcp_f32_e32 v18, v11
	v_div_fixup_f32 v1, v1, v15, 1.0
	v_mul_f32_e32 v10, v1, v13
	s_waitcnt lgkmcnt(1)
	v_mul_f32_e32 v1, v1, v6
	s_waitcnt lgkmcnt(0)
	v_mul_f32_e32 v6, v15, v8
	v_fma_f32 v8, -v11, v18, 1.0
	v_fmac_f32_e32 v18, v8, v18
	v_div_scale_f32 v8, vcc, 1.0, v17, 1.0
	v_mul_f32_e32 v20, v8, v18
	ds_write2_b32 v25, v12, v10 offset0:20 offset1:88
	v_fma_f32 v10, -v11, v20, v8
	v_fmac_f32_e32 v20, v10, v18
	v_add_u32_e32 v22, 0x2800, v4
	v_fma_f32 v8, -v11, v20, v8
	ds_read2_b32 v[10:11], v22 offset0:92 offset1:160
	ds_read2_b32 v[12:13], v25 offset0:156 offset1:224
	v_div_fmas_f32 v8, v8, v18, v20
	v_div_fixup_f32 v8, v8, v17, 1.0
	v_mul_f32_e32 v23, v17, v19
	v_mul_f32_e32 v7, v8, v7
	s_waitcnt lgkmcnt(0)
	v_mul_f32_e32 v18, v8, v12
	v_div_scale_f32 v8, s[0:1], v23, v23, 1.0
	v_rcp_f32_e32 v12, v8
	ds_write2_b32 v14, v1, v7 offset0:88 offset1:156
	v_mul_f32_e32 v1, v17, v9
	ds_write2_b32 v21, v6, v1 offset0:152 offset1:220
	v_fma_f32 v1, -v8, v12, 1.0
	v_fmac_f32_e32 v12, v1, v12
	v_div_scale_f32 v1, vcc, 1.0, v23, 1.0
	v_mul_f32_e32 v6, v1, v12
	v_fma_f32 v7, -v8, v6, v1
	v_fmac_f32_e32 v6, v7, v12
	v_fma_f32 v1, -v8, v6, v1
	v_mul_f32_e32 v10, v15, v10
	v_div_fmas_f32 v1, v1, v12, v6
	v_mul_f32_e32 v6, v17, v11
	v_div_fixup_f32 v1, v1, v23, 1.0
	ds_write2_b32 v22, v10, v6 offset0:92 offset1:160
	v_add_u32_e32 v22, 0x1800, v4
	v_mul_f32_e32 v17, v1, v13
	ds_read2_b32 v[6:7], v22 offset0:96 offset1:164
	v_add_u32_e32 v24, 0x800, v4
	ds_read2st64_b32 v[8:9], v4 offset0:77 offset1:78
	ds_read2_b32 v[10:11], v24 offset0:32 offset1:100
	ds_read2st64_b32 v[12:13], v4 offset0:79 offset1:80
	ds_read2st64_b32 v[14:15], v4 offset0:81 offset1:82
	ds_read_b32 v26, v4 offset:21248
	s_waitcnt lgkmcnt(4)
	v_mul_f32_e32 v8, v23, v8
	v_div_scale_f32 v19, s[0:1], v8, v8, 1.0
	v_rcp_f32_e32 v27, v19
	v_mul_f32_e32 v1, v1, v6
	s_waitcnt lgkmcnt(3)
	v_mul_f32_e32 v6, v23, v10
	ds_write2_b32 v25, v18, v17 offset0:156 offset1:224
	v_fma_f32 v10, -v19, v27, 1.0
	v_fmac_f32_e32 v27, v10, v27
	v_div_scale_f32 v10, vcc, 1.0, v8, 1.0
	v_mul_f32_e32 v17, v10, v27
	v_fma_f32 v18, -v19, v17, v10
	v_fmac_f32_e32 v17, v18, v27
	v_add_u32_e32 v25, 0x2a00, v4
	v_add_u32_e32 v28, 0x3c00, v4
	v_fma_f32 v10, -v19, v17, v10
	ds_read2_b32 v[18:19], v25 offset0:100 offset1:168
	ds_read2_b32 v[20:21], v28 offset0:36 offset1:104
	v_div_fmas_f32 v10, v10, v27, v17
	v_div_fixup_f32 v10, v10, v8, 1.0
	v_mul_f32_e32 v7, v10, v7
	s_waitcnt lgkmcnt(1)
	v_mul_f32_e32 v17, v23, v18
	s_waitcnt lgkmcnt(0)
	v_mul_f32_e32 v18, v10, v20
	v_mul_f32_e32 v20, v8, v9
	v_div_scale_f32 v9, s[0:1], v20, v20, 1.0
	v_rcp_f32_e32 v10, v9
	ds_write2_b32 v22, v1, v7 offset0:96 offset1:164
	v_mul_f32_e32 v1, v8, v11
	ds_write2_b32 v24, v6, v1 offset0:32 offset1:100
	v_fma_f32 v1, -v9, v10, 1.0
	v_fmac_f32_e32 v10, v1, v10
	v_div_scale_f32 v1, vcc, 1.0, v20, 1.0
	v_mul_f32_e32 v6, v1, v10
	v_fma_f32 v7, -v9, v6, v1
	v_fmac_f32_e32 v6, v7, v10
	v_fma_f32 v1, -v9, v6, v1
	v_div_fmas_f32 v1, v1, v10, v6
	v_mul_f32_e32 v6, v8, v19
	ds_write2_b32 v25, v17, v6 offset0:100 offset1:168
	v_add_u32_e32 v17, 0x1a00, v4
	v_mul_f32_e32 v12, v20, v12
	v_div_fixup_f32 v1, v1, v20, 1.0
	ds_read2_b32 v[6:7], v17 offset0:104 offset1:172
	ds_read2_b32 v[8:9], v24 offset0:168 offset1:236
	v_div_scale_f32 v11, s[0:1], v12, v12, 1.0
	v_mul_f32_e32 v10, v1, v21
	v_rcp_f32_e32 v21, v11
	s_waitcnt lgkmcnt(1)
	v_mul_f32_e32 v1, v1, v6
	s_waitcnt lgkmcnt(0)
	v_mul_f32_e32 v6, v20, v8
	ds_write2_b32 v28, v18, v10 offset0:36 offset1:104
	v_fma_f32 v8, -v11, v21, 1.0
	v_fmac_f32_e32 v21, v8, v21
	v_div_scale_f32 v8, vcc, 1.0, v12, 1.0
	v_mul_f32_e32 v22, v8, v21
	v_fma_f32 v10, -v11, v22, v8
	v_fmac_f32_e32 v22, v10, v21
	v_add_u32_e32 v23, 0x2c00, v4
	v_fma_f32 v8, -v11, v22, v8
	ds_read2_b32 v[10:11], v23 offset0:108 offset1:176
	ds_read2_b32 v[18:19], v28 offset0:172 offset1:240
	v_div_fmas_f32 v8, v8, v21, v22
	v_div_fixup_f32 v8, v8, v12, 1.0
	v_mul_f32_e32 v7, v8, v7
	s_waitcnt lgkmcnt(1)
	v_mul_f32_e32 v10, v20, v10
	v_mul_f32_e32 v20, v12, v13
	s_waitcnt lgkmcnt(0)
	v_mul_f32_e32 v18, v8, v18
	v_div_scale_f32 v8, s[0:1], v20, v20, 1.0
	v_rcp_f32_e32 v13, v8
	ds_write2_b32 v17, v1, v7 offset0:104 offset1:172
	v_mul_f32_e32 v1, v12, v9
	ds_write2_b32 v24, v6, v1 offset0:168 offset1:236
	v_fma_f32 v1, -v8, v13, 1.0
	v_fmac_f32_e32 v13, v1, v13
	v_div_scale_f32 v1, vcc, 1.0, v20, 1.0
	v_mul_f32_e32 v6, v1, v13
	v_fma_f32 v7, -v8, v6, v1
	v_fmac_f32_e32 v6, v7, v13
	v_fma_f32 v1, -v8, v6, v1
	v_div_fmas_f32 v1, v1, v13, v6
	v_div_fixup_f32 v1, v1, v20, 1.0
	v_mul_f32_e32 v6, v12, v11
	ds_write2_b32 v23, v10, v6 offset0:108 offset1:176
	v_mul_f32_e32 v10, v1, v19
	v_add_u32_e32 v17, 0x1c00, v4
	v_add_u32_e32 v19, 0xc00, v4
	v_mul_f32_e32 v14, v20, v14
	ds_read2_b32 v[6:7], v17 offset0:112 offset1:180
	ds_read2_b32 v[8:9], v19 offset0:48 offset1:116
	v_div_scale_f32 v11, s[0:1], v14, v14, 1.0
	v_rcp_f32_e32 v21, v11
	s_waitcnt lgkmcnt(1)
	v_mul_f32_e32 v1, v1, v6
	s_waitcnt lgkmcnt(0)
	v_mul_f32_e32 v6, v20, v8
	ds_write2_b32 v28, v18, v10 offset0:172 offset1:240
	v_fma_f32 v8, -v11, v21, 1.0
	v_fmac_f32_e32 v21, v8, v21
	v_div_scale_f32 v8, vcc, 1.0, v14, 1.0
	v_mul_f32_e32 v18, v8, v21
	v_add_u32_e32 v23, 0x4000, v4
	v_fma_f32 v10, -v11, v18, v8
	ds_read2_b32 v[12:13], v23 offset0:52 offset1:120
	v_fmac_f32_e32 v18, v10, v21
	v_fma_f32 v8, -v11, v18, v8
	v_div_fmas_f32 v8, v8, v21, v18
	v_div_fixup_f32 v8, v8, v14, 1.0
	v_mul_f32_e32 v15, v14, v15
	s_waitcnt lgkmcnt(0)
	v_mul_f32_e32 v12, v8, v12
	v_mul_f32_e32 v7, v8, v7
	v_div_scale_f32 v8, s[0:1], v15, v15, 1.0
	v_rcp_f32_e32 v18, v8
	ds_write2_b32 v17, v1, v7 offset0:112 offset1:180
	v_mul_f32_e32 v1, v14, v9
	ds_write2_b32 v19, v6, v1 offset0:48 offset1:116
	v_fma_f32 v1, -v8, v18, 1.0
	v_add_u32_e32 v22, 0x2e00, v4
	v_fmac_f32_e32 v18, v1, v18
	v_div_scale_f32 v1, vcc, 1.0, v15, 1.0
	ds_read2_b32 v[10:11], v22 offset0:116 offset1:184
	v_mul_f32_e32 v6, v1, v18
	v_fma_f32 v7, -v8, v6, v1
	v_fmac_f32_e32 v6, v7, v18
	v_fma_f32 v1, -v8, v6, v1
	v_div_fmas_f32 v1, v1, v18, v6
	s_waitcnt lgkmcnt(0)
	v_mul_f32_e32 v10, v20, v10
	v_div_fixup_f32 v1, v1, v15, 1.0
	v_mul_f32_e32 v6, v14, v11
	ds_write2_b32 v22, v10, v6 offset0:116 offset1:184
	v_mul_f32_e32 v10, v1, v13
	v_add_u32_e32 v11, 0x1e00, v4
	v_mul_f32_e32 v13, v15, v26
	ds_read2_b32 v[6:7], v11 offset0:120 offset1:188
	ds_read2_b32 v[8:9], v19 offset0:184 offset1:252
	v_div_scale_f32 v14, s[0:1], v13, v13, 1.0
	v_rcp_f32_e32 v17, v14
	s_waitcnt lgkmcnt(1)
	v_mul_f32_e32 v1, v1, v6
	s_waitcnt lgkmcnt(0)
	v_mul_f32_e32 v6, v15, v8
	ds_write2_b32 v23, v12, v10 offset0:52 offset1:120
	v_fma_f32 v8, -v14, v17, 1.0
	v_fmac_f32_e32 v17, v8, v17
	v_div_scale_f32 v8, vcc, 1.0, v13, 1.0
	v_mul_f32_e32 v10, v8, v17
	v_fma_f32 v12, -v14, v10, v8
	v_fmac_f32_e32 v10, v12, v17
	v_fma_f32 v8, -v14, v10, v8
	v_div_fmas_f32 v8, v8, v17, v10
	v_div_fixup_f32 v8, v8, v13, 1.0
	v_mul_f32_e32 v0, v8, v0
	ds_write_b32 v4, v0 offset:17136
	v_mul_f32_e32 v0, v8, v7
	v_mul_f32_e32 v2, v15, v2
	ds_write2_b32 v11, v1, v0 offset0:120 offset1:188
	v_mul_f32_e32 v0, v13, v9
	ds_write2_b32 v5, v2, v3 offset0:124 offset1:192
	ds_write2_b32 v19, v6, v0 offset0:184 offset1:252
	ds_write_b32 v4, v13 offset:27904
	v_lshl_add_u64 v[0:1], s[12:13], 0, v[156:157]
	v_add_co_u32_e32 v0, vcc, 0x4000, v0
	s_nop 1
	v_addc_co_u32_e32 v1, vcc, 0, v1, vcc
	global_store_dword v[0:1], v13, off offset:1408 nt

.LBB0_338:
	v_or_b32_e32 v9, s0, v20
	v_mul_u32_u24_e32 v8, 0x44, v9
	v_add3_u32 v6, s16, v8, v19
	v_add_u32_e32 v32, 0x5c00, v6
	s_waitcnt lgkmcnt(0)
	s_barrier
	ds_read2_b32 v[6:7], v32 offset1:4
	s_movk_i32 s2, 0xfef4
	v_lshlrev_b32_e32 v12, 2, v19
	v_mad_i32_i24 v10, v20, s2, v21
	s_lshl_b32 s2, s0, 2
	v_add3_u32 v12, v21, v12, s2
	ds_read_b128 v[24:27], v12
	v_add_u32_e32 v1, v10, v1
	v_add_u32_e32 v13, v10, v5
	v_add_u32_e32 v0, v10, v0
	v_add_u32_e32 v4, v10, v4
	ds_read_b32 v5, v1 offset:19456
	ds_read_b32 v23, v0 offset:19456
	ds_read_b32 v15, v4 offset:19456
	ds_read_b32 v13, v13 offset:19456
	ds_read_b128 v[28:31], v12 offset:64
	s_waitcnt lgkmcnt(4)
	v_mfma_f32_16x16x4_f32 v[24:27], v6, v5, v[24:27]
	ds_read2_b32 v[0:1], v32 offset0:8 offset1:12
	v_or_b32_e32 v12, s1, v20
	v_mul_u32_u24_e32 v21, 0x44, v12
	v_lshlrev_b32_e32 v156, 1, v19
	s_lshl_b32 s30, s0, 1
	s_mov_b64 s[2:3], -1
	s_and_b64 vcc, exec, s[14:15]
	s_waitcnt lgkmcnt(4)
	v_mfma_f32_16x16x4_f32 v[24:27], v7, v23, v[24:27]
	s_waitcnt lgkmcnt(0)
	v_mfma_f32_16x16x4_f32 v[24:27], v0, v15, v[24:27]
	v_add3_u32 v0, s16, v21, v19
	v_add_u32_e32 v4, 0x5c00, v0
	ds_read2_b32 v[6:7], v4 offset1:4
	ds_read2_b32 v[32:33], v4 offset0:8 offset1:12
	v_lshlrev_b32_e32 v0, 1, v18
	s_waitcnt lgkmcnt(1)
	v_mfma_f32_16x16x4_f32 v[28:31], v6, v5, v[28:31]
	v_mfma_f32_16x16x4_f32 v[28:31], v7, v23, v[28:31]
	v_mfma_f32_16x16x4_f32 v[24:27], v1, v13, v[24:27]
	v_mov_b32_e32 v1, v157
	v_lshl_add_u64 v[18:19], s[12:13], 0, v[0:1]
	v_lshl_add_u64 v[18:19], v[18:19], 0, v[156:157]
	v_lshl_add_u64 v[18:19], v[18:19], 0, s[30:31]
	s_waitcnt lgkmcnt(0)
	v_mfma_f32_16x16x4_f32 v[28:31], v32, v15, v[28:31]
	s_nop 3
	v_bfe_u32 v1, v24, 16, 1
	v_add3_u32 v1, v24, v1, s54
	v_bfe_u32 v4, v25, 16, 1
	v_add3_u32 v4, v25, v4, s54
	v_bfe_u32 v6, v26, 16, 1
	v_lshrrev_b32_e32 v1, 16, v1
	v_add3_u32 v7, v26, v6, s54
	v_and_or_b32 v6, v4, s33, v1
	v_bfe_u32 v4, v27, 16, 1
	v_add3_u32 v4, v27, v4, s54
	v_mfma_f32_16x16x4_f32 v[24:27], v33, v13, v[28:31]
	v_lshrrev_b32_e32 v1, 16, v7
	v_and_or_b32 v7, v4, s33, v1
	global_store_dwordx2 v[18:19], v[6:7], off nt
	s_nop 6
	v_bfe_u32 v1, v24, 16, 1
	v_add3_u32 v1, v24, v1, s54
	v_bfe_u32 v4, v25, 16, 1
	v_lshrrev_b32_e32 v1, 16, v1
	v_add3_u32 v4, v25, v4, s54
	v_and_or_b32 v6, v4, s33, v1
	v_bfe_u32 v1, v26, 16, 1
	v_add3_u32 v1, v26, v1, s54
	v_bfe_u32 v4, v27, 16, 1
	v_lshrrev_b32_e32 v1, 16, v1
	v_add3_u32 v4, v27, v4, s54
	v_and_or_b32 v7, v4, s33, v1
	global_store_dwordx2 v[18:19], v[6:7], off offset:32 nt
	s_cbranch_vccz .LBB0_340
	v_add_u32_e32 v1, 0x5800, v3
	ds_read2_b32 v[6:7], v1 offset1:4
	v_add_u32_e32 v4, 0x5000, v11
	ds_read2_b32 v[24:25], v4 offset1:16
	ds_read2_b32 v[26:27], v4 offset0:32 offset1:48
	v_mov_b32_e32 v19, v157
	s_mov_b64 s[2:3], 0
	s_waitcnt lgkmcnt(0)
	v_mfma_f32_16x16x4_f32 v[24:27], v6, v5, v[24:27]
	ds_read2_b32 v[4:5], v1 offset0:8 offset1:12
	v_mul_u32_u24_e32 v1, 24, v20
	v_lshlrev_b32_e32 v18, 1, v1
	v_lshl_add_u64 v[18:19], s[12:13], 0, v[18:19]
	v_lshl_add_u64 v[18:19], v[18:19], 0, v[156:157]
	v_mfma_f32_16x16x4_f32 v[24:27], v7, v23, v[24:27]
	s_waitcnt lgkmcnt(0)
	v_mfma_f32_16x16x4_f32 v[24:27], v4, v15, v[24:27]
	v_mfma_f32_16x16x4_f32 v[24:27], v5, v13, v[24:27]
	s_nop 9
	v_bfe_u32 v1, v24, 16, 1
	v_bfe_u32 v13, v26, 16, 1
	v_bfe_u32 v11, v25, 16, 1
	v_bfe_u32 v15, v27, 16, 1
	v_add3_u32 v1, v24, v1, s54
	v_add3_u32 v13, v26, v13, s54
	v_add3_u32 v11, v25, v11, s54
	v_add3_u32 v15, v27, v15, s54
	v_lshrrev_b32_e32 v1, 16, v1
	v_lshrrev_b32_e32 v13, 16, v13
	v_and_or_b32 v24, v11, s33, v1
	v_and_or_b32 v25, v15, s33, v13
	global_store_dwordx2 v[18:19], v[24:25], off offset:2176 nt
